# k9 plus the pv waves' rescale-factor (alpha) LDS reads for row groups 0-2 issued at the step start instead of serially per row group
# baseline (speedup 1.0000x reference)
; #define SBAR() __builtin_amdgcn_sched_barrier(0)
; __device__ __forceinline__ void attn_b2_unit(int b, int h, int qk, int jlo, const bf16_t* __restrict__ P, bf16_t* __restrict__ mix, const float* __restrict__ subg, float lam,
;                                              float* __restrict__ o0s, char* lds) {
;     ...
;                 const int j = jlo + s - 1;
;                 if (s >= 1 && j <= 2 * qk + 1) {
;                     const int pb = (s - 1) & 1;
;                     const int vb = vbl + pb * 32768;
;                     bf16x8 vf[2][4];
;                     {
;     ...
;                         const s16x4 a0 = tr_read<v_rd_off8(0, 0, 0)>(vb), b0 = tr_read<v_rd_off8(0, 0, 1)>(vb), a1 = tr_read<v_rd_off8(0, 1, 0)>(vb), b1 = tr_read<v_rd_off8(0, 1, 1)>(vb);
;                         const s16x4 a2 = tr_read<v_rd_off8(0, 2, 0)>(vb), b2 = tr_read<v_rd_off8(0, 2, 1)>(vb), a3 = tr_read<v_rd_off8(0, 3, 0)>(vb), b3 = tr_read<v_rd_off8(0, 3, 1)>(vb);
;                         const s16x4 c0_ = tr_read<v_rd_off8(1, 0, 0)>(vb), d0_ = tr_read<v_rd_off8(1, 0, 1)>(vb), c1_ = tr_read<v_rd_off8(1, 1, 0)>(vb), d1_ = tr_read<v_rd_off8(1, 1, 1)>(vb);
;                         const s16x4 c2_ = tr_read<v_rd_off8(1, 2, 0)>(vb), d2_ = tr_read<v_rd_off8(1, 2, 1)>(vb), c3_ = tr_read<v_rd_off8(1, 3, 0)>(vb), d3_ = tr_read<v_rd_off8(1, 3, 1)>(vb);
;                         asm volatile("s_waitcnt lgkmcnt(0)" ::: "memory"); SBAR();
;                         vf[0][0] = PKV(a0, b0); vf[0][1] = PKV(a1, b1); vf[0][2] = PKV(a2, b2); vf[0][3] = PKV(a3, b3);
;                         vf[1][0] = PKV(c0_, d0_); vf[1][1] = PKV(c1_, d1_); vf[1][2] = PKV(c2_, d2_); vf[1][3] = PKV(c3_, d3_);
;     ...
;                     }
; #pragma unroll
;                     for (int rg = 0; rg < 4; ++rg) {
;                         if (j <= 2 * qk + (rg >> 1)) {
;                             const float* al = (const float*)(lds + B2_A + ((pb * 4 + rg) * 32) * 4);
;                             const float amine = al[r32];
;                             if (__any(amine < 1.f)) { const float* alh = al + 4 * hi;
; #pragma unroll
;                                 for (int r = 0; r < 16; ++r) { const float a = alh[(r & 3) + 8 * (r >> 2)]; o[2 * rg][r] *= a; o[2 * rg + 1][r] *= a; }
.LBB0_368:
	s_add_i32 s3, s3, -1
	s_cmp_eq_u32 s2, 0
	s_cselect_b64 s[46:47], -1, 0
	s_cmp_gt_i32 s3, s72
	s_cselect_b64 s[48:49], -1, 0
	s_or_b64 s[46:47], s[46:47], s[48:49]
	s_and_b64 vcc, exec, s[46:47]
	s_cbranch_vccnz .LBB0_382
	s_andn2_b32 s46, 1, s2
	v_lshl_add_u32 v1, s46, 15, v209
	ds_read_b64_tr_b16 v[152:153], v1 offset:0
	ds_read_b64_tr_b16 v[154:155], v1 offset:0x1000
	ds_read_b64_tr_b16 v[148:149], v1 offset:0x2000
	ds_read_b64_tr_b16 v[150:151], v1 offset:0x3000
	ds_read_b64_tr_b16 v[6:7], v1 offset:0x4000
	ds_read_b64_tr_b16 v[8:9], v1 offset:0x5000
	ds_read_b64_tr_b16 v[2:3], v1 offset:0x6000
	ds_read_b64_tr_b16 v[4:5], v1 offset:0x7000
	ds_read_b64_tr_b16 v[160:161], v1 offset:0x200
	ds_read_b64_tr_b16 v[162:163], v1 offset:0x1200
	ds_read_b64_tr_b16 v[156:157], v1 offset:0x2200
	ds_read_b64_tr_b16 v[158:159], v1 offset:0x3200
	ds_read_b64_tr_b16 v[144:145], v1 offset:0x4200
	ds_read_b64_tr_b16 v[146:147], v1 offset:0x5200
	ds_read_b64_tr_b16 v[10:11], v1 offset:0x6200
	ds_read_b64_tr_b16 v[12:13], v1 offset:0x7200
	s_lshl_b32 s2, s46, 9
	s_add_i32 s2, s2, 0x20000
	v_lshl_add_u32 v228, v165, 2, s2
	ds_read_b32 v229, v228
	ds_read_b32 v230, v228 offset:128
	ds_read_b32 v231, v228 offset:256
	s_waitcnt lgkmcnt(0)
	s_cmp_le_i32 s3, s60
	s_cselect_b64 s[48:49], -1, 0
	s_cmp_gt_i32 s3, s60
	s_cbranch_scc1 .LBB0_373
	s_lshl_b32 s2, s46, 9
	s_add_i32 s2, s2, 0
	s_add_i32 s2, s2, 0x20000
	v_cmp_gt_f32_e32 vcc, 1.0, v229
	s_cbranch_vccz .LBB0_372
	v_add_u32_e32 v1, s2, v182
	ds_read_b128 v[212:215], v1 offset:96
	ds_read_b128 v[216:219], v1 offset:64
	ds_read_b128 v[220:223], v1 offset:32
	ds_read_b128 v[224:227], v1
	s_waitcnt lgkmcnt(0)
	v_pk_mul_f32 v[140:141], v[140:141], v[212:213]
	v_pk_mul_f32 v[136:137], v[136:137], v[216:217]
	v_pk_mul_f32 v[132:133], v[132:133], v[220:221]
	v_pk_mul_f32 v[142:143], v[142:143], v[214:215]
	v_pk_mul_f32 v[138:139], v[138:139], v[218:219]
	v_pk_mul_f32 v[134:135], v[134:135], v[222:223]
	v_pk_mul_f32 v[130:131], v[130:131], v[226:227]
	v_pk_mul_f32 v[128:129], v[128:129], v[224:225]
	v_pk_mul_f32 v[124:125], v[124:125], v[212:213]
	v_pk_mul_f32 v[120:121], v[120:121], v[216:217]
	v_pk_mul_f32 v[116:117], v[116:117], v[220:221]
	v_pk_mul_f32 v[126:127], v[126:127], v[214:215]
	v_pk_mul_f32 v[122:123], v[122:123], v[218:219]
	v_pk_mul_f32 v[118:119], v[118:119], v[222:223]
	v_pk_mul_f32 v[114:115], v[114:115], v[226:227]
	v_pk_mul_f32 v[112:113], v[112:113], v[224:225]

; __device__ __forceinline__ void attn_b2_unit(int b, int h, int qk, int jlo, const bf16_t* __restrict__ P, bf16_t* __restrict__ mix, const float* __restrict__ subg, float lam,
;                                              float* __restrict__ o0s, char* lds) {
;     ...
;                         if (j <= 2 * qk + (rg >> 1)) {
;                             const float* al = (const float*)(lds + B2_A + ((pb * 4 + rg) * 32) * 4);
;                             const float amine = al[r32];
;                             if (__any(amine < 1.f)) { const float* alh = al + 4 * hi;
; #pragma unroll
;                                 for (int r = 0; r < 16; ++r) { const float a = alh[(r & 3) + 8 * (r >> 2)]; o[2 * rg][r] *= a; o[2 * rg + 1][r] *= a; }
.LBB0_373:
	s_andn2_b64 vcc, exec, s[48:49]
	s_lshl_b32 s48, s46, 2
	s_cbranch_vccnz .LBB0_377
	s_or_b32 s2, s48, 1
	s_lshl_b32 s3, s2, 7
	s_add_i32 s3, s3, 0
	s_add_i32 s3, s3, 0x20000
	v_cmp_gt_f32_e32 vcc, 1.0, v230
	s_cbranch_vccz .LBB0_376
	v_add_u32_e32 v1, s3, v182
	ds_read_b128 v[212:215], v1 offset:96
	ds_read_b128 v[216:219], v1 offset:64
	ds_read_b128 v[220:223], v1 offset:32
	ds_read_b128 v[224:227], v1
	s_waitcnt lgkmcnt(0)
	v_pk_mul_f32 v[108:109], v[108:109], v[212:213]
	v_pk_mul_f32 v[104:105], v[104:105], v[216:217]
	v_pk_mul_f32 v[100:101], v[100:101], v[220:221]
	v_pk_mul_f32 v[110:111], v[110:111], v[214:215]
	v_pk_mul_f32 v[106:107], v[106:107], v[218:219]
	v_pk_mul_f32 v[102:103], v[102:103], v[222:223]
	v_pk_mul_f32 v[98:99], v[98:99], v[226:227]
	v_pk_mul_f32 v[96:97], v[96:97], v[224:225]
	v_pk_mul_f32 v[92:93], v[92:93], v[212:213]
	v_pk_mul_f32 v[88:89], v[88:89], v[216:217]
	v_pk_mul_f32 v[84:85], v[84:85], v[220:221]
	v_pk_mul_f32 v[94:95], v[94:95], v[214:215]
	v_pk_mul_f32 v[90:91], v[90:91], v[218:219]
	v_pk_mul_f32 v[86:87], v[86:87], v[222:223]
	v_pk_mul_f32 v[82:83], v[82:83], v[226:227]
	v_pk_mul_f32 v[80:81], v[80:81], v[224:225]

; __device__ __forceinline__ void attn_b2_unit(int b, int h, int qk, int jlo, const bf16_t* __restrict__ P, bf16_t* __restrict__ mix, const float* __restrict__ subg, float lam,
;                                              float* __restrict__ o0s, char* lds) {
;     ...
;                         if (j <= 2 * qk + (rg >> 1)) {
;                             const float* al = (const float*)(lds + B2_A + ((pb * 4 + rg) * 32) * 4);
;                             const float amine = al[r32];
;                             if (__any(amine < 1.f)) { const float* alh = al + 4 * hi;
; #pragma unroll
;                                 for (int r = 0; r < 16; ++r) { const float a = alh[(r & 3) + 8 * (r >> 2)]; o[2 * rg][r] *= a; o[2 * rg + 1][r] *= a; }
.LBB0_377:
	s_or_b32 s2, s48, 2
	s_lshl_b32 s3, s2, 7
	s_add_i32 s3, s3, 0
	s_add_i32 s3, s3, 0x20000
	v_cmp_gt_f32_e32 vcc, 1.0, v231
	s_cbranch_vccz .LBB0_379
	v_add_u32_e32 v1, s3, v182
	ds_read_b128 v[212:215], v1 offset:96
	ds_read_b128 v[216:219], v1 offset:64
	ds_read_b128 v[220:223], v1 offset:32
	ds_read_b128 v[224:227], v1
	s_waitcnt lgkmcnt(0)
	v_pk_mul_f32 v[76:77], v[76:77], v[212:213]
	v_pk_mul_f32 v[72:73], v[72:73], v[216:217]
	v_pk_mul_f32 v[68:69], v[68:69], v[220:221]
	v_pk_mul_f32 v[78:79], v[78:79], v[214:215]
	v_pk_mul_f32 v[74:75], v[74:75], v[218:219]
	v_pk_mul_f32 v[70:71], v[70:71], v[222:223]
	v_pk_mul_f32 v[66:67], v[66:67], v[226:227]
	v_pk_mul_f32 v[64:65], v[64:65], v[224:225]
	v_pk_mul_f32 v[60:61], v[60:61], v[212:213]
	v_pk_mul_f32 v[56:57], v[56:57], v[216:217]
	v_pk_mul_f32 v[52:53], v[52:53], v[220:221]
	v_pk_mul_f32 v[62:63], v[62:63], v[214:215]
	v_pk_mul_f32 v[58:59], v[58:59], v[218:219]
	v_pk_mul_f32 v[54:55], v[54:55], v[222:223]
	v_pk_mul_f32 v[50:51], v[50:51], v[226:227]
	v_pk_mul_f32 v[48:49], v[48:49], v[224:225]
